# hoist compiler-inserted vmcnt(0) out of the in_proj K-loop header to its preheader (template's counted vmcnt(6) protocol already covers the back edge)
# speedup vs baseline: 1.0008x; 1.0008x over previous
.LBB0_211:
	s_ashr_i32 s41, s40, 31
	v_cmp_lt_i64_e32 vcc, s[8:9], v[160:161]
	s_lshl_b64 s[8:9], s[40:41], 19
	s_add_u32 s42, s47, s8
	s_addc_u32 s43, s48, s9
	s_and_b64 s[8:9], vcc, exec
	s_cselect_b32 s1, s43, s3
	s_cselect_b32 s33, s42, s2
	s_ashr_i32 s39, s38, 31
	s_lshl_b64 s[8:9], s[38:39], 19
	s_add_u32 s44, s94, s8
	s_addc_u32 s45, s95, s9
	s_and_b64 s[8:9], vcc, exec
	s_cselect_b32 s39, s45, s7
	s_cselect_b32 s41, s44, s6
	s_add_u32 s2, s2, 0x40080
	s_addc_u32 s3, s3, 0
	s_add_u32 s71, s6, 0x100
	v_mov_b32_e32 v2, 0
	s_addc_u32 s72, s7, 0
	s_mov_b32 s73, -2
	v_mov_b32_e32 v3, v2
	v_mov_b32_e32 v4, v2
	v_mov_b32_e32 v5, v2
	v_mov_b32_e32 v6, v2
	v_mov_b32_e32 v7, v2
	v_mov_b32_e32 v8, v2
	v_mov_b32_e32 v9, v2
	v_mov_b32_e32 v10, v2
	v_mov_b32_e32 v11, v2
	v_mov_b32_e32 v12, v2
	v_mov_b32_e32 v13, v2
	v_mov_b32_e32 v18, v2
	v_mov_b32_e32 v19, v2
	v_mov_b32_e32 v20, v2
	v_mov_b32_e32 v21, v2
	v_mov_b32_e32 v26, v2
	v_mov_b32_e32 v27, v2
	v_mov_b32_e32 v28, v2
	v_mov_b32_e32 v29, v2
	v_mov_b32_e32 v34, v2
	v_mov_b32_e32 v35, v2
	v_mov_b32_e32 v36, v2
	v_mov_b32_e32 v37, v2
	v_mov_b32_e32 v42, v2
	v_mov_b32_e32 v43, v2
	v_mov_b32_e32 v44, v2
	v_mov_b32_e32 v45, v2
	v_mov_b32_e32 v50, v2
	v_mov_b32_e32 v51, v2
	v_mov_b32_e32 v52, v2
	v_mov_b32_e32 v53, v2
	v_mov_b32_e32 v14, v2
	v_mov_b32_e32 v15, v2
	v_mov_b32_e32 v16, v2
	v_mov_b32_e32 v17, v2
	v_mov_b32_e32 v22, v2
	v_mov_b32_e32 v23, v2
	v_mov_b32_e32 v24, v2
	v_mov_b32_e32 v25, v2
	v_mov_b32_e32 v30, v2
	v_mov_b32_e32 v31, v2
	v_mov_b32_e32 v32, v2
	v_mov_b32_e32 v33, v2
	v_mov_b32_e32 v38, v2
	v_mov_b32_e32 v39, v2
	v_mov_b32_e32 v40, v2
	v_mov_b32_e32 v41, v2
	v_mov_b32_e32 v46, v2
	v_mov_b32_e32 v47, v2
	v_mov_b32_e32 v48, v2
	v_mov_b32_e32 v49, v2
	v_mov_b32_e32 v54, v2
	v_mov_b32_e32 v55, v2
	v_mov_b32_e32 v56, v2
	v_mov_b32_e32 v57, v2
	v_mov_b32_e32 v58, v2
	v_mov_b32_e32 v59, v2
	v_mov_b32_e32 v60, v2
	v_mov_b32_e32 v61, v2
	v_mov_b32_e32 v62, v2
	v_mov_b32_e32 v63, v2
	v_mov_b32_e32 v64, v2
	v_mov_b32_e32 v65, v2
	v_mov_b32_e32 v66, v2
	v_mov_b32_e32 v67, v2
	v_mov_b32_e32 v68, v2
	v_mov_b32_e32 v69, v2
	v_mov_b32_e32 v70, v2
	v_mov_b32_e32 v71, v2
	v_mov_b32_e32 v72, v2
	v_mov_b32_e32 v73, v2
	v_mov_b32_e32 v74, v2
	v_mov_b32_e32 v75, v2
	v_mov_b32_e32 v76, v2
	v_mov_b32_e32 v77, v2
	v_mov_b32_e32 v82, v2
	v_mov_b32_e32 v83, v2
	v_mov_b32_e32 v84, v2
	v_mov_b32_e32 v85, v2
	v_mov_b32_e32 v90, v2
	v_mov_b32_e32 v91, v2
	v_mov_b32_e32 v92, v2
	v_mov_b32_e32 v93, v2
	v_mov_b32_e32 v98, v2
	v_mov_b32_e32 v99, v2
	v_mov_b32_e32 v100, v2
	v_mov_b32_e32 v101, v2
	v_mov_b32_e32 v106, v2
	v_mov_b32_e32 v107, v2
	v_mov_b32_e32 v108, v2
	v_mov_b32_e32 v109, v2
	v_mov_b32_e32 v114, v2
	v_mov_b32_e32 v115, v2
	v_mov_b32_e32 v116, v2
	v_mov_b32_e32 v117, v2
	v_mov_b32_e32 v78, v2
	v_mov_b32_e32 v79, v2
	v_mov_b32_e32 v80, v2
	v_mov_b32_e32 v81, v2
	v_mov_b32_e32 v86, v2
	v_mov_b32_e32 v87, v2
	v_mov_b32_e32 v88, v2
	v_mov_b32_e32 v89, v2
	v_mov_b32_e32 v94, v2
	v_mov_b32_e32 v95, v2
	v_mov_b32_e32 v96, v2
	v_mov_b32_e32 v97, v2
	v_mov_b32_e32 v102, v2
	v_mov_b32_e32 v103, v2
	v_mov_b32_e32 v104, v2
	v_mov_b32_e32 v105, v2
	v_mov_b32_e32 v110, v2
	v_mov_b32_e32 v111, v2
	v_mov_b32_e32 v112, v2
	v_mov_b32_e32 v113, v2
	v_mov_b32_e32 v118, v2
	v_mov_b32_e32 v119, v2
	v_mov_b32_e32 v120, v2
	v_mov_b32_e32 v121, v2
	v_mov_b32_e32 v122, v2
	v_mov_b32_e32 v123, v2
	v_mov_b32_e32 v124, v2
	v_mov_b32_e32 v125, v2
	v_mov_b32_e32 v126, v2
	v_mov_b32_e32 v127, v2
	v_mov_b32_e32 v128, v2
	v_mov_b32_e32 v129, v2
	s_waitcnt vmcnt(0)
.LBB0_212:
	ds_read_b128 v[130:133], v173
	ds_read_b128 v[134:137], v173 offset:1024
	ds_read_b128 v[138:141], v173 offset:2048
	ds_read_b128 v[142:145], v173 offset:3072
	s_add_u32 s6, s2, 0xfffc0080
	s_addc_u32 s7, s3, -1
	s_cmp_eq_u32 s73, 12
	s_cselect_b32 s9, s1, s7
	s_cselect_b32 s8, s33, s6
	s_cselect_b32 s7, s39, s72
	s_cselect_b32 s6, s41, s71
	v_lshl_add_u64 v[214:215], s[2:3], 0, v[156:157]
	s_add_i32 m0, s50, 0xc000
	ds_read_b128 v[180:183], v175
	ds_read_b128 v[184:187], v175 offset:1024
	ds_read_b128 v[190:193], v175 offset:2048
	ds_read_b128 v[194:197], v175 offset:3072
	ds_read_b128 v[198:201], v175 offset:4096
	ds_read_b128 v[202:205], v175 offset:5120
	ds_read_b128 v[206:209], v175 offset:6144
	ds_read_b128 v[210:213], v175 offset:7168
	global_load_lds_dwordx4 v[214:215], off
	v_lshl_add_u64 v[214:215], s[2:3], 0, v[158:159]
	s_add_i32 m0, s50, 0xe000
	s_nop 0
	global_load_lds_dwordx4 v[214:215], off
	s_waitcnt lgkmcnt(8)
	s_barrier
	s_waitcnt lgkmcnt(0)
	s_setprio 1
	s_waitcnt lgkmcnt(0)
	v_mfma_f32_16x16x32_bf16 v[126:129], v[130:133], v[180:183], v[126:129]
	v_mfma_f32_16x16x32_bf16 v[122:125], v[138:141], v[180:183], v[122:125]
	v_mfma_f32_16x16x32_bf16 v[118:121], v[130:133], v[190:193], v[118:121]
	v_mfma_f32_16x16x32_bf16 v[110:113], v[138:141], v[190:193], v[110:113]
	v_mfma_f32_16x16x32_bf16 v[102:105], v[130:133], v[198:201], v[102:105]
	v_mfma_f32_16x16x32_bf16 v[94:97], v[138:141], v[198:201], v[94:97]
	v_mfma_f32_16x16x32_bf16 v[86:89], v[130:133], v[206:209], v[86:89]
	v_mfma_f32_16x16x32_bf16 v[78:81], v[138:141], v[206:209], v[78:81]
	v_mfma_f32_16x16x32_bf16 v[126:129], v[134:137], v[184:187], v[126:129]
	v_mfma_f32_16x16x32_bf16 v[122:125], v[142:145], v[184:187], v[122:125]
	v_mfma_f32_16x16x32_bf16 v[118:121], v[134:137], v[194:197], v[118:121]
	v_mfma_f32_16x16x32_bf16 v[110:113], v[142:145], v[194:197], v[110:113]
	v_mfma_f32_16x16x32_bf16 v[102:105], v[134:137], v[202:205], v[102:105]
	v_mfma_f32_16x16x32_bf16 v[94:97], v[142:145], v[202:205], v[94:97]
	v_mfma_f32_16x16x32_bf16 v[86:89], v[134:137], v[210:213], v[86:89]
	v_mfma_f32_16x16x32_bf16 v[78:81], v[142:145], v[210:213], v[78:81]
	s_setprio 0
	s_barrier
	s_add_i32 s74, s66, s49
	v_lshl_add_u64 v[230:231], s[6:7], 0, v[148:149]
	s_mov_b32 m0, s74
	ds_read_b128 v[214:217], v177
	ds_read_b128 v[218:221], v177 offset:1024
	ds_read_b128 v[222:225], v177 offset:2048
	ds_read_b128 v[226:229], v177 offset:3072
	global_load_lds_dwordx4 v[230:231], off
	v_lshl_add_u64 v[232:233], s[6:7], 0, v[152:153]
	s_add_i32 m0, s74, 0x2000
	s_nop 0
	global_load_lds_dwordx4 v[232:233], off
	s_barrier
	s_waitcnt lgkmcnt(0)
	s_setprio 1
	s_waitcnt lgkmcnt(0)
	v_mfma_f32_16x16x32_bf16 v[114:117], v[214:217], v[180:183], v[114:117]
	v_mfma_f32_16x16x32_bf16 v[106:109], v[222:225], v[180:183], v[106:109]
	v_mfma_f32_16x16x32_bf16 v[98:101], v[214:217], v[190:193], v[98:101]
	v_mfma_f32_16x16x32_bf16 v[90:93], v[222:225], v[190:193], v[90:93]
	v_mfma_f32_16x16x32_bf16 v[82:85], v[214:217], v[198:201], v[82:85]
	v_mfma_f32_16x16x32_bf16 v[74:77], v[222:225], v[198:201], v[74:77]
	v_mfma_f32_16x16x32_bf16 v[70:73], v[214:217], v[206:209], v[70:73]
	v_mfma_f32_16x16x32_bf16 v[66:69], v[222:225], v[206:209], v[66:69]
	v_mfma_f32_16x16x32_bf16 v[114:117], v[218:221], v[184:187], v[114:117]
	v_mfma_f32_16x16x32_bf16 v[106:109], v[226:229], v[184:187], v[106:109]
	v_mfma_f32_16x16x32_bf16 v[98:101], v[218:221], v[194:197], v[98:101]
	v_mfma_f32_16x16x32_bf16 v[90:93], v[226:229], v[194:197], v[90:93]
	v_mfma_f32_16x16x32_bf16 v[82:85], v[218:221], v[202:205], v[82:85]
	v_mfma_f32_16x16x32_bf16 v[74:77], v[226:229], v[202:205], v[74:77]
	v_mfma_f32_16x16x32_bf16 v[70:73], v[218:221], v[210:213], v[70:73]
	v_mfma_f32_16x16x32_bf16 v[66:69], v[226:229], v[210:213], v[66:69]
	s_setprio 0
	s_mov_b32 m0, s50
	v_lshl_add_u64 v[234:235], s[8:9], 0, v[146:147]
	s_barrier
	ds_read_b128 v[180:183], v175 offset:16384
	ds_read_b128 v[184:187], v175 offset:17408
	ds_read_b128 v[190:193], v175 offset:18432
	ds_read_b128 v[194:197], v175 offset:19456
	ds_read_b128 v[198:201], v175 offset:20480
	ds_read_b128 v[202:205], v175 offset:21504
	ds_read_b128 v[206:209], v175 offset:22528
	ds_read_b128 v[210:213], v175 offset:23552
	global_load_lds_dwordx4 v[234:235], off
	v_lshl_add_u64 v[236:237], s[8:9], 0, v[150:151]
	s_mov_b32 m0, s51
	s_nop 0
	global_load_lds_dwordx4 v[236:237], off
	s_barrier
	s_waitcnt lgkmcnt(0)
	s_setprio 1
	s_waitcnt lgkmcnt(0)
	v_mfma_f32_16x16x32_bf16 v[62:65], v[130:133], v[180:183], v[62:65]
	v_mfma_f32_16x16x32_bf16 v[58:61], v[138:141], v[180:183], v[58:61]
	v_mfma_f32_16x16x32_bf16 v[54:57], v[130:133], v[190:193], v[54:57]
	v_mfma_f32_16x16x32_bf16 v[46:49], v[138:141], v[190:193], v[46:49]
	v_mfma_f32_16x16x32_bf16 v[38:41], v[130:133], v[198:201], v[38:41]
	v_mfma_f32_16x16x32_bf16 v[30:33], v[138:141], v[198:201], v[30:33]
	v_mfma_f32_16x16x32_bf16 v[22:25], v[130:133], v[206:209], v[22:25]
	v_mfma_f32_16x16x32_bf16 v[14:17], v[138:141], v[206:209], v[14:17]
	v_mfma_f32_16x16x32_bf16 v[62:65], v[134:137], v[184:187], v[62:65]
	v_mfma_f32_16x16x32_bf16 v[58:61], v[142:145], v[184:187], v[58:61]
	v_mfma_f32_16x16x32_bf16 v[54:57], v[134:137], v[194:197], v[54:57]
	v_mfma_f32_16x16x32_bf16 v[46:49], v[142:145], v[194:197], v[46:49]
	v_mfma_f32_16x16x32_bf16 v[38:41], v[134:137], v[202:205], v[38:41]
	v_mfma_f32_16x16x32_bf16 v[30:33], v[142:145], v[202:205], v[30:33]
	v_mfma_f32_16x16x32_bf16 v[22:25], v[134:137], v[210:213], v[22:25]
	v_mfma_f32_16x16x32_bf16 v[14:17], v[142:145], v[210:213], v[14:17]
	s_setprio 0
	s_barrier
	s_add_u32 s74, s6, 0x40000
	s_addc_u32 s75, s7, 0
	s_add_i32 s76, s67, s49
	v_lshl_add_u64 v[130:131], s[74:75], 0, v[148:149]
	s_mov_b32 m0, s76
	s_nop 0
	global_load_lds_dwordx4 v[130:131], off
	v_lshl_add_u64 v[130:131], s[74:75], 0, v[152:153]
	s_add_i32 m0, s76, 0x2000
	s_nop 0
	global_load_lds_dwordx4 v[130:131], off
	s_waitcnt vmcnt(6)
	s_barrier
	s_setprio 1
	v_mfma_f32_16x16x32_bf16 v[50:53], v[214:217], v[180:183], v[50:53]
	v_mfma_f32_16x16x32_bf16 v[42:45], v[222:225], v[180:183], v[42:45]
	v_mfma_f32_16x16x32_bf16 v[34:37], v[214:217], v[190:193], v[34:37]
	v_mfma_f32_16x16x32_bf16 v[26:29], v[222:225], v[190:193], v[26:29]
	v_mfma_f32_16x16x32_bf16 v[18:21], v[214:217], v[198:201], v[18:21]
	v_mfma_f32_16x16x32_bf16 v[10:13], v[222:225], v[198:201], v[10:13]
	v_mfma_f32_16x16x32_bf16 v[6:9], v[214:217], v[206:209], v[6:9]
	v_mfma_f32_16x16x32_bf16 v[2:5], v[222:225], v[206:209], v[2:5]
	v_mfma_f32_16x16x32_bf16 v[50:53], v[218:221], v[184:187], v[50:53]
	v_mfma_f32_16x16x32_bf16 v[42:45], v[226:229], v[184:187], v[42:45]
	v_mfma_f32_16x16x32_bf16 v[34:37], v[218:221], v[194:197], v[34:37]
	v_mfma_f32_16x16x32_bf16 v[26:29], v[226:229], v[194:197], v[26:29]
	v_mfma_f32_16x16x32_bf16 v[18:21], v[218:221], v[202:205], v[18:21]
	v_mfma_f32_16x16x32_bf16 v[10:13], v[226:229], v[202:205], v[10:13]
	v_mfma_f32_16x16x32_bf16 v[6:9], v[218:221], v[210:213], v[6:9]
	v_mfma_f32_16x16x32_bf16 v[2:5], v[226:229], v[210:213], v[2:5]
	s_setprio 0
	s_add_i32 s74, 0, 0x18000
	v_add_u32_e32 v142, s74, v171
	s_barrier
	ds_read_b128 v[130:133], v142
	ds_read_b128 v[134:137], v142 offset:1024
	ds_read_b128 v[138:141], v142 offset:2048
	ds_read_b128 v[142:145], v142 offset:3072
	s_add_u32 s8, s8, 0x40000
	s_addc_u32 s9, s9, 0
	s_mov_b32 m0, s52
	v_lshl_add_u64 v[214:215], s[8:9], 0, v[146:147]
	ds_read_b128 v[180:183], v175 offset:32768
	ds_read_b128 v[184:187], v175 offset:33792
	ds_read_b128 v[190:193], v175 offset:34816
	ds_read_b128 v[194:197], v175 offset:35840
	ds_read_b128 v[198:201], v175 offset:36864
	ds_read_b128 v[202:205], v175 offset:37888
	ds_read_b128 v[206:209], v175 offset:38912
	ds_read_b128 v[210:213], v175 offset:39936
	global_load_lds_dwordx4 v[214:215], off
	v_lshl_add_u64 v[214:215], s[8:9], 0, v[150:151]
	s_mov_b32 m0, s53
	s_nop 0
	global_load_lds_dwordx4 v[214:215], off
	s_waitcnt lgkmcnt(8)
	s_barrier
	s_waitcnt lgkmcnt(0)
	s_setprio 1
	s_waitcnt lgkmcnt(0)
	v_mfma_f32_16x16x32_bf16 v[126:129], v[130:133], v[180:183], v[126:129]
	v_mfma_f32_16x16x32_bf16 v[122:125], v[138:141], v[180:183], v[122:125]
	v_mfma_f32_16x16x32_bf16 v[118:121], v[130:133], v[190:193], v[118:121]
	v_mfma_f32_16x16x32_bf16 v[110:113], v[138:141], v[190:193], v[110:113]
	v_mfma_f32_16x16x32_bf16 v[102:105], v[130:133], v[198:201], v[102:105]
	v_mfma_f32_16x16x32_bf16 v[94:97], v[138:141], v[198:201], v[94:97]
	v_mfma_f32_16x16x32_bf16 v[86:89], v[130:133], v[206:209], v[86:89]
	v_mfma_f32_16x16x32_bf16 v[78:81], v[138:141], v[206:209], v[78:81]
	v_mfma_f32_16x16x32_bf16 v[126:129], v[134:137], v[184:187], v[126:129]
	v_mfma_f32_16x16x32_bf16 v[122:125], v[142:145], v[184:187], v[122:125]
	v_mfma_f32_16x16x32_bf16 v[118:121], v[134:137], v[194:197], v[118:121]
	v_mfma_f32_16x16x32_bf16 v[110:113], v[142:145], v[194:197], v[110:113]
	v_mfma_f32_16x16x32_bf16 v[102:105], v[134:137], v[202:205], v[102:105]
	v_mfma_f32_16x16x32_bf16 v[94:97], v[142:145], v[202:205], v[94:97]
	v_mfma_f32_16x16x32_bf16 v[86:89], v[134:137], v[210:213], v[86:89]
	v_mfma_f32_16x16x32_bf16 v[78:81], v[142:145], v[210:213], v[78:81]
	s_setprio 0
	s_barrier
	s_add_i32 s8, 0, 0x1c000
	s_add_i32 s9, s74, s49
	v_add_u32_e32 v154, s8, v171
	v_lshl_add_u64 v[230:231], v[230:231], 0, s[26:27]
	s_mov_b32 m0, s9
	ds_read_b128 v[214:217], v154
	ds_read_b128 v[218:221], v154 offset:1024
	ds_read_b128 v[222:225], v154 offset:2048
	ds_read_b128 v[226:229], v154 offset:3072
	global_load_lds_dwordx4 v[230:231], off
	v_lshl_add_u64 v[230:231], v[232:233], 0, s[26:27]
	s_add_i32 m0, s9, 0x2000
	s_nop 0
	global_load_lds_dwordx4 v[230:231], off
	s_barrier
	s_waitcnt lgkmcnt(0)
	s_setprio 1
	s_waitcnt lgkmcnt(0)
	v_mfma_f32_16x16x32_bf16 v[114:117], v[214:217], v[180:183], v[114:117]
	v_mfma_f32_16x16x32_bf16 v[106:109], v[222:225], v[180:183], v[106:109]
	v_mfma_f32_16x16x32_bf16 v[98:101], v[214:217], v[190:193], v[98:101]
	v_mfma_f32_16x16x32_bf16 v[90:93], v[222:225], v[190:193], v[90:93]
	v_mfma_f32_16x16x32_bf16 v[82:85], v[214:217], v[198:201], v[82:85]
	v_mfma_f32_16x16x32_bf16 v[74:77], v[222:225], v[198:201], v[74:77]
	v_mfma_f32_16x16x32_bf16 v[70:73], v[214:217], v[206:209], v[70:73]
	v_mfma_f32_16x16x32_bf16 v[66:69], v[222:225], v[206:209], v[66:69]
	v_mfma_f32_16x16x32_bf16 v[114:117], v[218:221], v[184:187], v[114:117]
	v_mfma_f32_16x16x32_bf16 v[106:109], v[226:229], v[184:187], v[106:109]
	v_mfma_f32_16x16x32_bf16 v[98:101], v[218:221], v[194:197], v[98:101]
	v_mfma_f32_16x16x32_bf16 v[90:93], v[226:229], v[194:197], v[90:93]
	v_mfma_f32_16x16x32_bf16 v[82:85], v[218:221], v[202:205], v[82:85]
	v_mfma_f32_16x16x32_bf16 v[74:77], v[226:229], v[202:205], v[74:77]
	v_mfma_f32_16x16x32_bf16 v[70:73], v[218:221], v[210:213], v[70:73]
	v_mfma_f32_16x16x32_bf16 v[66:69], v[226:229], v[210:213], v[66:69]
	s_setprio 0
	s_mov_b32 m0, s56
	v_lshl_add_u64 v[230:231], v[234:235], 0, s[26:27]
	s_barrier
	ds_read_b128 v[180:183], v175 offset:49152
	ds_read_b128 v[184:187], v175 offset:50176
	ds_read_b128 v[190:193], v175 offset:51200
	ds_read_b128 v[194:197], v175 offset:52224
	ds_read_b128 v[198:201], v175 offset:53248
	ds_read_b128 v[202:205], v175 offset:54272
	ds_read_b128 v[206:209], v175 offset:55296
	ds_read_b128 v[210:213], v175 offset:56320
	global_load_lds_dwordx4 v[230:231], off
	v_lshl_add_u64 v[230:231], v[236:237], 0, s[26:27]
	s_mov_b32 m0, s57
	s_nop 0
	global_load_lds_dwordx4 v[230:231], off
	s_barrier
	s_waitcnt lgkmcnt(0)
	s_setprio 1
	s_waitcnt lgkmcnt(0)
	v_mfma_f32_16x16x32_bf16 v[62:65], v[130:133], v[180:183], v[62:65]
	v_mfma_f32_16x16x32_bf16 v[58:61], v[138:141], v[180:183], v[58:61]
	v_mfma_f32_16x16x32_bf16 v[54:57], v[130:133], v[190:193], v[54:57]
	v_mfma_f32_16x16x32_bf16 v[46:49], v[138:141], v[190:193], v[46:49]
	v_mfma_f32_16x16x32_bf16 v[38:41], v[130:133], v[198:201], v[38:41]
	v_mfma_f32_16x16x32_bf16 v[30:33], v[138:141], v[198:201], v[30:33]
	v_mfma_f32_16x16x32_bf16 v[22:25], v[130:133], v[206:209], v[22:25]
	v_mfma_f32_16x16x32_bf16 v[14:17], v[138:141], v[206:209], v[14:17]
	v_mfma_f32_16x16x32_bf16 v[62:65], v[134:137], v[184:187], v[62:65]
	v_mfma_f32_16x16x32_bf16 v[58:61], v[142:145], v[184:187], v[58:61]
	v_mfma_f32_16x16x32_bf16 v[54:57], v[134:137], v[194:197], v[54:57]
	v_mfma_f32_16x16x32_bf16 v[46:49], v[142:145], v[194:197], v[46:49]
	v_mfma_f32_16x16x32_bf16 v[38:41], v[134:137], v[202:205], v[38:41]
	v_mfma_f32_16x16x32_bf16 v[30:33], v[142:145], v[202:205], v[30:33]
	v_mfma_f32_16x16x32_bf16 v[22:25], v[134:137], v[210:213], v[22:25]
	v_mfma_f32_16x16x32_bf16 v[14:17], v[142:145], v[210:213], v[14:17]
	s_setprio 0
	s_barrier
	s_add_u32 s6, s6, 0x40080
	s_addc_u32 s7, s7, 0
	s_add_i32 s8, s8, s49
	v_lshl_add_u64 v[130:131], s[6:7], 0, v[148:149]
	s_mov_b32 m0, s8
	s_nop 0
	global_load_lds_dwordx4 v[130:131], off
	v_lshl_add_u64 v[130:131], s[6:7], 0, v[152:153]
	s_add_i32 m0, s8, 0x2000
	s_nop 0
	global_load_lds_dwordx4 v[130:131], off
	s_waitcnt vmcnt(6)
	s_barrier
	s_setprio 1
	v_mfma_f32_16x16x32_bf16 v[50:53], v[214:217], v[180:183], v[50:53]
	v_mfma_f32_16x16x32_bf16 v[42:45], v[222:225], v[180:183], v[42:45]
	v_mfma_f32_16x16x32_bf16 v[34:37], v[214:217], v[190:193], v[34:37]
	v_mfma_f32_16x16x32_bf16 v[26:29], v[222:225], v[190:193], v[26:29]
	v_mfma_f32_16x16x32_bf16 v[18:21], v[214:217], v[198:201], v[18:21]
	v_mfma_f32_16x16x32_bf16 v[10:13], v[222:225], v[198:201], v[10:13]
	v_mfma_f32_16x16x32_bf16 v[6:9], v[214:217], v[206:209], v[6:9]
	v_mfma_f32_16x16x32_bf16 v[2:5], v[222:225], v[206:209], v[2:5]
	v_mfma_f32_16x16x32_bf16 v[50:53], v[218:221], v[184:187], v[50:53]
	v_mfma_f32_16x16x32_bf16 v[42:45], v[226:229], v[184:187], v[42:45]
	v_mfma_f32_16x16x32_bf16 v[34:37], v[218:221], v[194:197], v[34:37]
	v_mfma_f32_16x16x32_bf16 v[26:29], v[226:229], v[194:197], v[26:29]
	v_mfma_f32_16x16x32_bf16 v[18:21], v[218:221], v[202:205], v[18:21]
	v_mfma_f32_16x16x32_bf16 v[10:13], v[226:229], v[202:205], v[10:13]
	v_mfma_f32_16x16x32_bf16 v[6:9], v[218:221], v[210:213], v[6:9]
	v_mfma_f32_16x16x32_bf16 v[2:5], v[226:229], v[210:213], v[2:5]
	s_setprio 0
	s_add_i32 s73, s73, 2
	s_add_u32 s2, s2, 0x100
	s_addc_u32 s3, s3, 0
	s_add_u32 s71, s71, 0x100
	s_addc_u32 s72, s72, 0
	s_cmp_gt_u32 s73, 13
	s_barrier
	s_cbranch_scc0 .LBB0_212
	v_mov_b32_e32 v154, v167
	v_mov_b32_e32 v194, v169
	s_cmp_lt_i32 s70, 16
	v_add_u32_e32 v182, s55, v154
	v_lshl_add_u32 v180, s0, 8, v182
	v_ashrrev_i32_e32 v181, 31, v180
	v_lshl_add_u64 v[130:131], v[180:181], 2, s[62:63]
	global_load_dword v178, v[130:131], off
	global_load_dword v176, v[130:131], off offset:64
	global_load_dword v174, v[130:131], off offset:128
	global_load_dword v172, v[130:131], off offset:192
	global_load_dword v170, v[130:131], off offset:512
	global_load_dword v168, v[130:131], off offset:576
	global_load_dword v166, v[130:131], off offset:640
	global_load_dword v164, v[130:131], off offset:704
	s_mov_b64 s[2:3], -1
	s_cbranch_scc0 .LBB0_226
	v_lshl_add_u32 v183, v194, 2, s58
	v_lshl_add_u32 v186, s70, 6, v183
	v_ashrrev_i32_e32 v187, 31, v186
	v_readlane_b32 s8, v248, 18
	v_lshlrev_b64 v[184:185], 2, v[186:187]
	v_readlane_b32 s20, v248, 30
	v_readlane_b32 s21, v248, 31
	v_lshl_add_u64 v[134:135], s[34:35], 0, v[184:185]
	s_cmp_lg_u32 s0, 64
	v_lshl_add_u64 v[130:131], s[20:21], 0, v[184:185]
	global_load_dwordx4 v[130:133], v[130:131], off
	s_nop 0
	global_load_dwordx4 v[138:141], v[134:135], off
	v_lshl_add_u64 v[134:135], s[36:37], 0, v[184:185]
	global_load_dwordx4 v[134:137], v[134:135], off
	v_readlane_b32 s9, v248, 19
	v_readlane_b32 s10, v248, 20
	v_readlane_b32 s11, v248, 21
	v_readlane_b32 s12, v248, 22
	v_readlane_b32 s13, v248, 23
	v_readlane_b32 s14, v248, 24
	v_readlane_b32 s15, v248, 25
	v_readlane_b32 s16, v248, 26
	v_readlane_b32 s17, v248, 27
	v_readlane_b32 s18, v248, 28
	v_readlane_b32 s19, v248, 29
	v_readlane_b32 s22, v248, 32
	v_readlane_b32 s23, v248, 33
	s_cbranch_scc0 .LBB0_223
	v_cmp_lt_i32_e32 vcc, 13, v154
	v_lshlrev_b32_e32 v192, 2, v183
	s_waitcnt vmcnt(0)
	v_mul_f32_e32 v188, v164, v164
	v_pk_mul_f32 v[190:191], v[14:15], v[6:7]
	s_and_saveexec_b64 s[2:3], vcc
	s_cbranch_execz .LBB0_218
	v_pk_mul_f32 v[144:145], v[80:81], v[72:73]
	v_pk_mul_f32 v[142:143], v[78:79], v[70:71]
	v_mul_f32_e32 v196, v172, v172
	v_add_lshl_u32 v193, s59, v154, 8
	s_add_i32 s1, 0, 0x20010
	v_pk_mul_f32 v[142:143], v[142:143], v[196:197] op_sel_hi:[1,0]
	v_pk_mul_f32 v[144:145], v[144:145], v[196:197] op_sel_hi:[1,0]
	v_add3_u32 v195, s1, v193, v192
	v_readlane_b32 s6, v248, 43
	ds_write_b128 v195, v[142:145]
	v_pk_mul_f32 v[144:145], v[16:17], v[8:9]
	v_readlane_b32 s7, v248, 44
	v_pk_mul_f32 v[142:143], v[190:191], v[188:189] op_sel_hi:[1,0]
	v_pk_mul_f32 v[144:145], v[144:145], v[188:189] op_sel_hi:[1,0]
	v_add3_u32 v193, s68, v193, v192
	s_andn2_b64 vcc, exec, s[6:7]
	ds_write_b128 v193, v[142:145]
	s_cbranch_vccnz .LBB0_218
	s_lshl_b32 s1, s0, 1
	v_add3_u32 v196, s1, -14, v154
	v_ashrrev_i32_e32 v197, 31, v196
	v_readlane_b32 s6, v248, 47
	v_lshlrev_b64 v[196:197], 12, v[196:197]
	v_readlane_b32 s7, v248, 48
	s_nop 1
	v_lshl_add_u64 v[196:197], s[6:7], 0, v[196:197]
	v_lshl_add_u64 v[196:197], v[186:187], 2, v[196:197]
	global_store_dwordx4 v[196:197], v[142:145], off
